# hg scan unit boundary no longer drains the output stores (latch waits removed, top wait only for units with state loads)
# speedup vs baseline: 1.0133x; 1.0117x over previous
; __device__ __forceinline__ void hg_block(ArgsP a_, int jl, unsigned char* smem) { const ArgsP a = a_;
;     ...
;     for (int uu = 0; uu < ntot_; ++uu) { const int u = cb < 64 ? uu : uu % nunits; const int un_ = cb < 64 ? uu + 1 : (uu + 1) % nunits;
;     ...
;         u32x2 gcur[4];
; #pragma unroll
;         for (int vt = 0; vt < 4; ++vt) gcur[vt] = gpre[vt];
.LBB0_390:
	s_add_i32 s58, s58, 64
	s_add_i32 s60, s60, s59
	s_cmp_lg_u32 s56, s49
	v_mov_b64_e32 v[124:125], v[132:133]
	v_mov_b64_e32 v[104:105], v[130:131]
	v_mov_b64_e32 v[94:95], v[128:129]
	v_mov_b64_e32 v[84:85], v[126:127]
	s_mov_b32 s65, s49
	s_cbranch_scc0 .LBB0_442

; #define HG_DECODE(u, b_, h_, ck_, smp_, row0_, len_) do { if (cb < 64) { b_ = cb >> 3; h_ = cb & 7; ck_ = (u); smp_ = false; row0_ = b_ * TP + 64 * ck_; len_ = ck_ < 32 ? 64 : 16; } \
;         else { const int it_ = (cb - 64) + (u) * (G - 64); b_ = it_ >> 3; h_ = it_ & 7; ck_ = 0; smp_ = true; row0_ = RP + 8 * b_; len_ = 8; } } while (0)
; __device__ __forceinline__ void hg_block(ArgsP a_, int jl, unsigned char* smem) { const ArgsP a = a_;
;     ...
;         int b, h, ck, row0, len; bool sample; HG_DECODE(u, b, h, ck, sample, row0, len);
;         const bool first = sample || ck == 0, last = sample || ck == 32;
;         if (first) state_load<128, 128>(S, AIN(2) + (((size_t)jl * 128 + b) * 8 + h) * 16384, 128, wid, fr, fq, !sample);
.LBB0_412:
	s_and_b64 vcc, exec, s[40:41]
	s_cbranch_vccnz .Lhg_top_wait
	s_cmp_lg_u32 s65, 0
	s_cbranch_scc1 .Lhg_top_nowait

; __device__ __forceinline__ void hg_block(ArgsP a_, int jl, unsigned char* smem) { const ArgsP a = a_;
;     ...
;         { f32x4 run = {0.f, 0.f, 0.f, 0.f};
; #pragma unroll
;           for (int r = 0; r < 4; ++r) { run = run + lf4[r]; cs[r] = run; }
;           *(f32x4*)(TOT + rg * 128 + c4) = run; }
;         __syncthreads();
;         { f32x4 pre = {0.f, 0.f, 0.f, 0.f}, gmid = pre, glast = pre;
; #pragma unroll
;           for (int k = 0; k < 16; ++k) { const f32x4 t = *(const f32x4*)(TOT + k * 128 + c4); if (k < rg) pre = pre + t; if (k < 8) gmid = gmid + t; glast = glast + t; }
;           f32x4 Emid, Elm;
; #pragma unroll
;           for (int e = 0; e < 4; ++e) { Emid[e] = __expf(gmid[e]); Elm[e] = __expf(glast[e] - gmid[e]); }
.Lhg_top_nowait:
	s_cmp_eq_u32 s64, 64
	s_cbranch_scc1 .Lhg_mask_done
	v_cmp_gt_i32_e32 vcc, s64, v136
	s_nop 1
	v_cndmask_b32_e32 v0, 0, v0, vcc
	v_cndmask_b32_e32 v1, 0, v1, vcc
	v_cndmask_b32_e32 v2, 0, v2, vcc
	v_cndmask_b32_e32 v3, 0, v3, vcc
	v_cndmask_b32_e32 v82, 0, v82, vcc
	v_cndmask_b32_e32 v83, 0, v83, vcc
	v_cndmask_b32_e32 v78, 0, v78, vcc
	v_cndmask_b32_e32 v79, 0, v79, vcc
	v_cndmask_b32_e32 v80, 0, v80, vcc
	v_cndmask_b32_e32 v81, 0, v81, vcc
	v_cmp_gt_i32_e32 vcc, s64, v107
	s_nop 1
	v_cndmask_b32_e32 v4, 0, v4, vcc
	v_cndmask_b32_e32 v5, 0, v5, vcc
	v_cndmask_b32_e32 v6, 0, v6, vcc
	v_cndmask_b32_e32 v7, 0, v7, vcc
	v_cndmask_b32_e32 v90, 0, v90, vcc
	v_cndmask_b32_e32 v91, 0, v91, vcc
	v_cndmask_b32_e32 v86, 0, v86, vcc
	v_cndmask_b32_e32 v87, 0, v87, vcc
	v_cndmask_b32_e32 v88, 0, v88, vcc
	v_cndmask_b32_e32 v89, 0, v89, vcc
	v_cmp_gt_i32_e32 vcc, s64, v109
	s_nop 1
	v_cndmask_b32_e32 v8, 0, v8, vcc
	v_cndmask_b32_e32 v9, 0, v9, vcc
	v_cndmask_b32_e32 v10, 0, v10, vcc
	v_cndmask_b32_e32 v11, 0, v11, vcc
	v_cndmask_b32_e32 v102, 0, v102, vcc
	v_cndmask_b32_e32 v103, 0, v103, vcc
	v_cndmask_b32_e32 v98, 0, v98, vcc
	v_cndmask_b32_e32 v99, 0, v99, vcc
	v_cndmask_b32_e32 v100, 0, v100, vcc
	v_cndmask_b32_e32 v101, 0, v101, vcc
	v_cmp_gt_i32_e32 vcc, s64, v164
	s_nop 1
	v_cndmask_b32_e32 v12, 0, v12, vcc
	v_cndmask_b32_e32 v13, 0, v13, vcc
	v_cndmask_b32_e32 v14, 0, v14, vcc
	v_cndmask_b32_e32 v15, 0, v15, vcc
	v_cndmask_b32_e32 v120, 0, v120, vcc
	v_cndmask_b32_e32 v121, 0, v121, vcc
	v_cndmask_b32_e32 v110, 0, v110, vcc
	v_cndmask_b32_e32 v111, 0, v111, vcc
	v_cndmask_b32_e32 v112, 0, v112, vcc
	v_cndmask_b32_e32 v113, 0, v113, vcc
.Lhg_mask_done:
	v_pk_add_f32 v[62:63], v[2:3], 0 op_sel_hi:[1,0]
	v_pk_add_f32 v[64:65], v[0:1], 0 op_sel_hi:[1,0]
	v_pk_add_f32 v[58:59], v[62:63], v[6:7]
	v_pk_add_f32 v[60:61], v[64:65], v[4:5]
	v_pk_add_f32 v[54:55], v[58:59], v[10:11]
	v_pk_add_f32 v[56:57], v[60:61], v[8:9]
	v_pk_add_f32 v[52:53], v[54:55], v[14:15]
	v_pk_add_f32 v[50:51], v[56:57], v[12:13]
	ds_write_b128 v168, v[50:53]
	s_waitcnt lgkmcnt(0)
	s_barrier
	ds_read_b128 v[202:205], v135
	ds_read_b128 v[206:209], v135 offset:512
	ds_read_b128 v[210:213], v135 offset:1024
	ds_read_b128 v[214:217], v135 offset:1536
	ds_read_b128 v[218:221], v135 offset:2048
	ds_read_b128 v[222:225], v135 offset:2560
	ds_read_b128 v[226:229], v135 offset:3072
	ds_read_b128 v[230:233], v135 offset:3584
	ds_read_b128 v[234:237], v135 offset:4096
	ds_read_b128 v[238:241], v135 offset:4608
	ds_read_b128 v[242:245], v135 offset:5120
	ds_read_b128 v[246:249], v135 offset:5632
	v_lshlrev_b32_e32 v175, 16, v78
	v_and_b32_e32 v178, 0xffff0000, v79
	s_mov_b32 s49, 0xffff0000
	s_waitcnt lgkmcnt(11)
	v_pk_add_f32 v[70:71], v[204:205], 0 op_sel_hi:[1,0]
	v_pk_add_f32 v[72:73], v[202:203], 0 op_sel_hi:[1,0]
	ds_read_b128 v[202:205], v135 offset:6144
	v_cndmask_b32_e64 v75, 0, v73, s[66:67]
	v_cndmask_b32_e64 v74, 0, v72, s[66:67]
	v_cndmask_b32_e64 v77, 0, v71, s[66:67]
	v_cndmask_b32_e64 v76, 0, v70, s[66:67]
	s_waitcnt lgkmcnt(11)
	v_pk_add_f32 v[126:127], v[206:207], v[74:75]
	v_pk_add_f32 v[128:129], v[208:209], v[76:77]
	v_pk_add_f32 v[70:71], v[70:71], v[208:209]
	v_pk_add_f32 v[72:73], v[72:73], v[206:207]
	ds_read_b128 v[206:209], v135 offset:6656
	v_cndmask_b32_e64 v75, v75, v127, s[68:69]
	v_cndmask_b32_e64 v74, v74, v126, s[68:69]
	v_cndmask_b32_e64 v77, v77, v129, s[68:69]
	v_cndmask_b32_e64 v76, v76, v128, s[68:69]
	s_waitcnt lgkmcnt(11)
	v_pk_add_f32 v[126:127], v[210:211], v[74:75]
	v_pk_add_f32 v[128:129], v[212:213], v[76:77]
	v_pk_add_f32 v[70:71], v[70:71], v[212:213]
	v_pk_add_f32 v[72:73], v[72:73], v[210:211]
	ds_read_b128 v[210:213], v135 offset:7168
	v_cndmask_b32_e64 v75, v75, v127, s[70:71]
	v_cndmask_b32_e64 v74, v74, v126, s[70:71]
	v_cndmask_b32_e64 v77, v77, v129, s[70:71]
	v_cndmask_b32_e64 v76, v76, v128, s[70:71]
	s_waitcnt lgkmcnt(11)
	v_pk_add_f32 v[126:127], v[214:215], v[74:75]
	v_pk_add_f32 v[128:129], v[216:217], v[76:77]
	v_pk_add_f32 v[70:71], v[70:71], v[216:217]
	v_pk_add_f32 v[72:73], v[72:73], v[214:215]
	ds_read_b128 v[214:217], v135 offset:7680
	v_cndmask_b32_e64 v75, v75, v127, s[72:73]
	v_cndmask_b32_e64 v74, v74, v126, s[72:73]
	v_cndmask_b32_e64 v77, v77, v129, s[72:73]
	v_cndmask_b32_e64 v76, v76, v128, s[72:73]
	s_waitcnt lgkmcnt(11)
	v_pk_add_f32 v[126:127], v[218:219], v[74:75]
	v_pk_add_f32 v[128:129], v[220:221], v[76:77]
	v_pk_add_f32 v[70:71], v[70:71], v[220:221]
	v_pk_add_f32 v[72:73], v[72:73], v[218:219]
	v_cndmask_b32_e64 v75, v75, v127, s[74:75]
	v_cndmask_b32_e64 v74, v74, v126, s[74:75]
	v_cndmask_b32_e64 v77, v77, v129, s[74:75]
	v_cndmask_b32_e64 v76, v76, v128, s[74:75]
	s_waitcnt lgkmcnt(10)
	v_pk_add_f32 v[126:127], v[222:223], v[74:75]
	v_pk_add_f32 v[128:129], v[224:225], v[76:77]
	v_pk_add_f32 v[70:71], v[70:71], v[224:225]
	v_pk_add_f32 v[72:73], v[72:73], v[222:223]
	v_cndmask_b32_e64 v75, v75, v127, s[76:77]
	v_cndmask_b32_e64 v74, v74, v126, s[76:77]
	v_cndmask_b32_e64 v77, v77, v129, s[76:77]
	v_cndmask_b32_e64 v76, v76, v128, s[76:77]
	s_waitcnt lgkmcnt(9)
	v_pk_add_f32 v[126:127], v[226:227], v[74:75]
	v_pk_add_f32 v[128:129], v[228:229], v[76:77]
	v_cndmask_b32_e64 v75, v75, v127, s[78:79]
	v_cndmask_b32_e64 v74, v74, v126, s[78:79]
	v_pk_add_f32 v[126:127], v[70:71], v[228:229]
	v_cndmask_b32_e64 v77, v77, v129, s[78:79]
	v_cndmask_b32_e64 v76, v76, v128, s[78:79]
	v_pk_add_f32 v[72:73], v[72:73], v[226:227]
	s_waitcnt lgkmcnt(8)
; __device__ __forceinline__ unsigned cvt_pk_bf16(float lo, float hi) { unsigned r; asm("v_cvt_pk_bf16_f32 %0, %1, %2" : "=v"(r) : "v"(lo), "v"(hi)); return r; }
; __device__ __forceinline__ void hg_block(ArgsP a_, int jl, unsigned char* smem) { const ArgsP a = a_;
;     ...
;           for (int k = 0; k < 16; ++k) { const f32x4 t = *(const f32x4*)(TOT + k * 128 + c4); if (k < rg) pre = pre + t; if (k < 8) gmid = gmid + t; glast = glast + t; }
;           f32x4 Emid, Elm;
; #pragma unroll
;           for (int e = 0; e < 4; ++e) { Emid[e] = __expf(gmid[e]); Elm[e] = __expf(glast[e] - gmid[e]); }
;           float ktv[4][4];
; #pragma unroll
;           for (int r = 0; r < 4; ++r) { const int i = 4 * rg + r; const f32x4 d = pre + cs[r] - gmid;
;               const f32x4 q = {__uint_as_float(q2[r].x << 16), __uint_as_float(q2[r].x & 0xffff0000u), __uint_as_float(q2[r].y << 16), __uint_as_float(q2[r].y & 0xffff0000u)};
;               const f32x4 kk = {__uint_as_float(kk2[r].x << 16), __uint_as_float(kk2[r].x & 0xffff0000u), __uint_as_float(kk2[r].y << 16), __uint_as_float(kk2[r].y & 0xffff0000u)};
;               f32x4 qa, qs, kb;
; #pragma unroll
;               for (int e = 0; e < 4; ++e) { const float eq = __expf(d[e]), ek = __expf(-d[e]); qa[e] = q[e] * eq; qs[e] = qa[e] * Emid[e]; kb[e] = kk[e] * ek; ktv[r][e] = kb[e] * Elm[e]; }
;               *(u32x2*)(QA + i * LQ + c4) = (u32x2){cvt_pk_bf16(qa[0], qa[1]), cvt_pk_bf16(qa[2], qa[3])};
;               *(u32x2*)(QS + i * LQ + c4) = (u32x2){cvt_pk_bf16(qs[0], qs[1]), cvt_pk_bf16(qs[2], qs[3])};
;               *(u32x2*)(KB + i * LQ + c4) = (u32x2){cvt_pk_bf16(kb[0], kb[1]), cvt_pk_bf16(kb[2], kb[3])}; }
	v_pk_add_f32 v[66:67], v[230:231], v[74:75]
	v_pk_add_f32 v[128:129], v[232:233], v[76:77]
	v_cndmask_b32_e64 v75, v75, v67, s[80:81]
	v_cndmask_b32_e64 v74, v74, v66, s[80:81]
	v_pk_add_f32 v[66:67], v[126:127], v[232:233]
	v_pk_add_f32 v[68:69], v[72:73], v[230:231]
	v_cndmask_b32_e64 v77, v77, v129, s[80:81]
	v_cndmask_b32_e64 v76, v76, v128, s[80:81]
	v_mul_f32_e32 v16, 0x3fb8aa3b, v68
	v_mul_f32_e32 v119, 0x3fb8aa3b, v66
	s_waitcnt lgkmcnt(7)
	v_pk_add_f32 v[126:127], v[234:235], v[74:75]
	v_pk_add_f32 v[128:129], v[236:237], v[76:77]
	v_cndmask_b32_e64 v75, v75, v127, s[82:83]
	v_cndmask_b32_e64 v74, v74, v126, s[82:83]
	v_cndmask_b32_e64 v77, v77, v129, s[82:83]
	v_cndmask_b32_e64 v76, v76, v128, s[82:83]
	v_pk_add_f32 v[126:127], v[66:67], v[236:237]
	v_pk_add_f32 v[128:129], v[68:69], v[234:235]
	v_exp_f32_e32 v16, v16
	v_exp_f32_e32 v119, v119
	s_waitcnt lgkmcnt(6)
	v_pk_add_f32 v[130:131], v[238:239], v[74:75]
	v_pk_add_f32 v[132:133], v[240:241], v[76:77]
	v_pk_add_f32 v[126:127], v[126:127], v[240:241]
	v_pk_add_f32 v[128:129], v[128:129], v[238:239]
	v_cndmask_b32_e64 v75, v75, v131, s[84:85]
	v_cndmask_b32_e64 v74, v74, v130, s[84:85]
	v_cndmask_b32_e64 v77, v77, v133, s[84:85]
	v_cndmask_b32_e64 v76, v76, v132, s[84:85]
	s_waitcnt lgkmcnt(5)
	v_pk_add_f32 v[130:131], v[242:243], v[74:75]
	v_pk_add_f32 v[132:133], v[244:245], v[76:77]
	v_pk_add_f32 v[126:127], v[126:127], v[244:245]
	v_pk_add_f32 v[128:129], v[128:129], v[242:243]
	v_cndmask_b32_e64 v75, v75, v131, s[86:87]
	v_cndmask_b32_e64 v74, v74, v130, s[86:87]
	v_cndmask_b32_e64 v77, v77, v133, s[86:87]
	v_cndmask_b32_e64 v76, v76, v132, s[86:87]
	s_waitcnt lgkmcnt(4)
	v_pk_add_f32 v[130:131], v[246:247], v[74:75]
	v_pk_add_f32 v[132:133], v[248:249], v[76:77]
	v_pk_add_f32 v[126:127], v[126:127], v[248:249]
	v_pk_add_f32 v[128:129], v[128:129], v[246:247]
	v_cndmask_b32_e64 v75, v75, v131, s[88:89]
	v_cndmask_b32_e64 v74, v74, v130, s[88:89]
	v_cndmask_b32_e64 v77, v77, v133, s[88:89]
	v_cndmask_b32_e64 v76, v76, v132, s[88:89]
	s_waitcnt lgkmcnt(3)
	v_pk_add_f32 v[130:131], v[202:203], v[74:75]
	v_pk_add_f32 v[132:133], v[204:205], v[76:77]
	v_pk_add_f32 v[126:127], v[126:127], v[204:205]
	v_pk_add_f32 v[128:129], v[128:129], v[202:203]
	v_cndmask_b32_e64 v75, v75, v131, s[90:91]
	v_cndmask_b32_e64 v74, v74, v130, s[90:91]
	v_cndmask_b32_e64 v77, v77, v133, s[90:91]
	v_cndmask_b32_e64 v76, v76, v132, s[90:91]
	s_waitcnt lgkmcnt(2)
	v_pk_add_f32 v[130:131], v[206:207], v[74:75]
	v_pk_add_f32 v[132:133], v[208:209], v[76:77]
	v_pk_add_f32 v[126:127], v[126:127], v[208:209]
	v_pk_add_f32 v[128:129], v[128:129], v[206:207]
	v_cndmask_b32_e64 v75, v75, v131, s[92:93]
	v_cndmask_b32_e64 v74, v74, v130, s[92:93]
	v_cndmask_b32_e64 v77, v77, v133, s[92:93]
	v_cndmask_b32_e64 v76, v76, v132, s[92:93]
	s_waitcnt lgkmcnt(1)
	v_pk_add_f32 v[130:131], v[210:211], v[74:75]
	v_pk_add_f32 v[132:133], v[212:213], v[76:77]
	v_cndmask_b32_e64 v131, v75, v131, s[94:95]
	v_cndmask_b32_e64 v130, v74, v130, s[94:95]
	v_pk_add_f32 v[126:127], v[126:127], v[212:213]
	v_cndmask_b32_e64 v77, v77, v133, s[94:95]
	v_cndmask_b32_e64 v76, v76, v132, s[94:95]
	v_pk_add_f32 v[128:129], v[128:129], v[210:211]
	s_waitcnt lgkmcnt(0)
	v_pk_add_f32 v[132:133], v[214:215], v[130:131]
	v_pk_add_f32 v[72:73], v[128:129], v[214:215]
	v_cndmask_b32_e64 v129, v130, v132, s[96:97]
	v_add_f32_e32 v64, v64, v129
	v_sub_f32_e32 v64, v64, v68
	v_mul_f32_e32 v179, 0x3fb8aa3b, v64
	v_mul_f32_e32 v64, 0xbfb8aa3b, v64
	v_exp_f32_e32 v64, v64
	v_cndmask_b32_e64 v128, v131, v133, s[96:97]
	v_pk_add_f32 v[176:177], v[216:217], v[76:77]
	v_pk_add_f32 v[70:71], v[126:127], v[216:217]
	v_mul_f32_e32 v175, v64, v175
	v_add_f32_e32 v64, v65, v128
	v_sub_f32_e32 v64, v64, v69
	v_mul_f32_e32 v65, 0x3fb8aa3b, v64
	v_mul_f32_e32 v64, 0xbfb8aa3b, v64
	v_exp_f32_e32 v64, v64
	v_cndmask_b32_e64 v76, v76, v176, s[96:97]
	v_add_f32_e32 v62, v62, v76
	v_and_b32_e32 v176, 0xffff0000, v78
	v_sub_f32_e32 v62, v62, v66
	v_mul_f32_e32 v176, v64, v176
	v_mul_f32_e32 v64, 0x3fb8aa3b, v62
	v_mul_f32_e32 v62, 0xbfb8aa3b, v62
	v_exp_f32_e32 v62, v62
	v_cndmask_b32_e64 v77, v77, v177, s[96:97]
	v_lshlrev_b32_e32 v177, 16, v79
	v_sub_f32_e32 v74, v72, v68
	v_mul_f32_e32 v177, v62, v177
	v_add_f32_e32 v62, v63, v77
	v_sub_f32_e32 v62, v62, v67
	v_mul_f32_e32 v63, 0x3fb8aa3b, v62
	v_mul_f32_e32 v75, 0x3fb8aa3b, v69
	v_mul_f32_e32 v126, 0x3fb8aa3b, v67
	v_exp_f32_e32 v179, v179
	v_exp_f32_e32 v65, v65
	v_exp_f32_e32 v64, v64
	v_exp_f32_e32 v63, v63
	v_mul_f32_e32 v74, 0x3fb8aa3b, v74
	v_exp_f32_e32 v75, v75
	v_exp_f32_e32 v126, v126
	v_mul_f32_e32 v62, 0xbfb8aa3b, v62
	v_exp_f32_e32 v74, v74
	v_exp_f32_e32 v62, v62
	v_lshlrev_b32_e32 v130, 16, v80
	v_and_b32_e32 v131, 0xffff0000, v80
	v_lshlrev_b32_e32 v132, 16, v81
	v_and_b32_e32 v133, 0xffff0000, v81
	v_mul_f32_e32 v130, v179, v130
	v_mul_f32_e32 v65, v65, v131
	v_mul_f32_e32 v64, v64, v132
	v_mul_f32_e32 v63, v63, v133
	v_add_f32_e32 v60, v60, v129
	v_mul_f32_e32 v179, v16, v130
	v_mul_f32_e32 v131, v75, v65
	v_mul_f32_e32 v132, v119, v64
	v_mul_f32_e32 v133, v126, v63
	v_cvt_pk_bf16_f32 v63, v64, v63
	v_cvt_pk_bf16_f32 v64, v179, v131
	v_sub_f32_e32 v60, v60, v68
	v_mul_f32_e32 v180, v74, v175
	v_mul_f32_e32 v178, v62, v178
	v_cvt_pk_bf16_f32 v62, v130, v65
	v_cvt_pk_bf16_f32 v65, v132, v133
	ds_write_b64 v106, v[64:65] offset:34816
	v_cvt_pk_bf16_f32 v64, v175, v176
	v_mul_f32_e32 v175, 0x3fb8aa3b, v60
	v_mul_f32_e32 v60, 0xbfb8aa3b, v60
	v_exp_f32_e32 v60, v60
	v_lshlrev_b32_e32 v130, 16, v86
	v_add_f32_e32 v58, v58, v76
	v_and_b32_e32 v131, 0xffff0000, v86
	v_mul_f32_e32 v130, v60, v130
; __device__ __forceinline__ unsigned cvt_pk_bf16(float lo, float hi) { unsigned r; asm("v_cvt_pk_bf16_f32 %0, %1, %2" : "=v"(r) : "v"(lo), "v"(hi)); return r; }
; __device__ __forceinline__ void hg_block(ArgsP a_, int jl, unsigned char* smem) { const ArgsP a = a_;
;     ...
;           for (int r = 0; r < 4; ++r) { const int i = 4 * rg + r; const f32x4 d = pre + cs[r] - gmid;
;               const f32x4 q = {__uint_as_float(q2[r].x << 16), __uint_as_float(q2[r].x & 0xffff0000u), __uint_as_float(q2[r].y << 16), __uint_as_float(q2[r].y & 0xffff0000u)};
;               const f32x4 kk = {__uint_as_float(kk2[r].x << 16), __uint_as_float(kk2[r].x & 0xffff0000u), __uint_as_float(kk2[r].y << 16), __uint_as_float(kk2[r].y & 0xffff0000u)};
;               f32x4 qa, qs, kb;
; #pragma unroll
;               for (int e = 0; e < 4; ++e) { const float eq = __expf(d[e]), ek = __expf(-d[e]); qa[e] = q[e] * eq; qs[e] = qa[e] * Emid[e]; kb[e] = kk[e] * ek; ktv[r][e] = kb[e] * Elm[e]; }
;               *(u32x2*)(QA + i * LQ + c4) = (u32x2){cvt_pk_bf16(qa[0], qa[1]), cvt_pk_bf16(qa[2], qa[3])};
;               *(u32x2*)(QS + i * LQ + c4) = (u32x2){cvt_pk_bf16(qs[0], qs[1]), cvt_pk_bf16(qs[2], qs[3])};
;               *(u32x2*)(KB + i * LQ + c4) = (u32x2){cvt_pk_bf16(kb[0], kb[1]), cvt_pk_bf16(kb[2], kb[3])}; }
; #pragma unroll
;           for (int e = 0; e < 4; ++e) {
;               *(u32x2*)(KT + (c4 + e) * LJ + 4 * rg) = (u32x2){cvt_pk_bf16(ktv[0][e], ktv[1][e]), cvt_pk_bf16(ktv[2][e], ktv[3][e])};
;               unsigned vv[4];
; #pragma unroll
;               for (int r = 0; r < 4; ++r) { const unsigned w = (e < 2) ? v2[r].x : v2[r].y; vv[r] = (e & 1) ? (w >> 16) : (w & 0xffffu); }
;               *(u32x2*)(VT + (c4 + e) * LJ + 4 * rg) = (u32x2){vv[0] | (vv[1] << 16), vv[2] | (vv[3] << 16)}; }
;           if (rg == 0) { f32x4 sd;
; #pragma unroll
;               for (int e = 0; e < 4; ++e) sd[e] = __expf(glast[e]);
;               *(f32x4*)(SDEC + c4) = sd; } }
	v_add_f32_e32 v60, v61, v128
	v_sub_f32_e32 v60, v60, v69
	v_mul_f32_e32 v61, 0x3fb8aa3b, v60
	v_mul_f32_e32 v60, 0xbfb8aa3b, v60
	v_exp_f32_e32 v60, v60
	v_sub_f32_e32 v58, v58, v66
	v_lshlrev_b32_e32 v132, 16, v87
	v_sub_f32_e32 v117, v73, v69
	v_mul_f32_e32 v131, v60, v131
	v_mul_f32_e32 v60, 0x3fb8aa3b, v58
	v_mul_f32_e32 v58, 0xbfb8aa3b, v58
	v_exp_f32_e32 v58, v58
	v_exp_f32_e32 v175, v175
	v_exp_f32_e32 v61, v61
	v_exp_f32_e32 v60, v60
	v_mul_f32_e32 v132, v58, v132
	v_add_f32_e32 v58, v59, v77
	v_sub_f32_e32 v58, v58, v67
	v_mul_f32_e32 v59, 0x3fb8aa3b, v58
	v_exp_f32_e32 v59, v59
	v_mul_f32_e32 v117, 0x3fb8aa3b, v117
	v_mul_f32_e32 v58, 0xbfb8aa3b, v58
	v_exp_f32_e32 v117, v117
	v_cvt_pk_bf16_f32 v65, v177, v178
	v_exp_f32_e32 v58, v58
	ds_write2st64_b64 v106, v[62:63], v[64:65] offset1:34
	v_lshlrev_b32_e32 v62, 16, v88
	v_and_b32_e32 v63, 0xffff0000, v88
	v_lshlrev_b32_e32 v64, 16, v89
	v_and_b32_e32 v65, 0xffff0000, v89
	v_mul_f32_e32 v62, v175, v62
	v_mul_f32_e32 v61, v61, v63
	v_mul_f32_e32 v60, v60, v64
	v_mul_f32_e32 v59, v59, v65
	v_add_f32_e32 v56, v56, v129
	v_and_b32_e32 v133, 0xffff0000, v87
	v_mul_f32_e32 v175, v16, v62
	v_mul_f32_e32 v63, v75, v61
	v_mul_f32_e32 v64, v119, v60
	v_mul_f32_e32 v65, v126, v59
	v_cvt_pk_bf16_f32 v59, v60, v59
	v_cvt_pk_bf16_f32 v60, v175, v63
	v_sub_f32_e32 v56, v56, v68
	v_mul_f32_e32 v181, v117, v176
	v_mul_f32_e32 v176, v74, v130
	v_mul_f32_e32 v133, v58, v133
	v_cvt_pk_bf16_f32 v58, v62, v61
	v_cvt_pk_bf16_f32 v61, v64, v65
	ds_write_b64 v108, v[60:61] offset:34816
	v_cvt_pk_bf16_f32 v60, v130, v131
	v_mul_f32_e32 v130, 0x3fb8aa3b, v56
	v_mul_f32_e32 v56, 0xbfb8aa3b, v56
	v_exp_f32_e32 v56, v56
	v_lshlrev_b32_e32 v62, 16, v98
	v_add_f32_e32 v54, v54, v76
	v_and_b32_e32 v63, 0xffff0000, v98
	v_mul_f32_e32 v62, v56, v62
	v_add_f32_e32 v56, v57, v128
	v_sub_f32_e32 v56, v56, v69
	v_mul_f32_e32 v57, 0x3fb8aa3b, v56
	v_mul_f32_e32 v56, 0xbfb8aa3b, v56
	v_exp_f32_e32 v56, v56
	v_sub_f32_e32 v54, v54, v66
	v_lshlrev_b32_e32 v64, 16, v99
	v_sub_f32_e32 v123, v70, v66
	v_mul_f32_e32 v63, v56, v63
	v_mul_f32_e32 v56, 0x3fb8aa3b, v54
	v_mul_f32_e32 v54, 0xbfb8aa3b, v54
	v_exp_f32_e32 v54, v54
	v_exp_f32_e32 v130, v130
	v_exp_f32_e32 v57, v57
	v_exp_f32_e32 v56, v56
	v_mul_f32_e32 v64, v54, v64
	v_add_f32_e32 v54, v55, v77
	v_sub_f32_e32 v54, v54, v67
	v_mul_f32_e32 v55, 0x3fb8aa3b, v54
	v_exp_f32_e32 v55, v55
	v_mul_f32_e32 v123, 0x3fb8aa3b, v123
	v_mul_f32_e32 v54, 0xbfb8aa3b, v54
	v_exp_f32_e32 v123, v123
	v_cvt_pk_bf16_f32 v61, v132, v133
	v_exp_f32_e32 v54, v54
	ds_write2st64_b64 v108, v[58:59], v[60:61] offset1:34
	v_lshlrev_b32_e32 v58, 16, v100
	v_and_b32_e32 v59, 0xffff0000, v100
	v_lshlrev_b32_e32 v60, 16, v101
	v_and_b32_e32 v61, 0xffff0000, v101
	v_mul_f32_e32 v58, v130, v58
	v_mul_f32_e32 v57, v57, v59
	v_mul_f32_e32 v56, v56, v60
	v_mul_f32_e32 v55, v55, v61
	v_add_f32_e32 v50, v50, v129
	v_and_b32_e32 v65, 0xffff0000, v99
	v_mul_f32_e32 v130, v16, v58
	v_mul_f32_e32 v59, v75, v57
	v_mul_f32_e32 v60, v119, v56
	v_mul_f32_e32 v61, v126, v55
	v_cvt_pk_bf16_f32 v55, v56, v55
	v_cvt_pk_bf16_f32 v56, v130, v59
	v_sub_f32_e32 v50, v50, v68
	v_mul_f32_e32 v182, v123, v177
	v_mul_f32_e32 v177, v117, v131
	v_mul_f32_e32 v131, v74, v62
	v_mul_f32_e32 v65, v54, v65
	v_cvt_pk_bf16_f32 v54, v58, v57
	v_cvt_pk_bf16_f32 v57, v60, v61
	ds_write_b64 v147, v[56:57] offset:34816
	v_cvt_pk_bf16_f32 v56, v62, v63
	v_mul_f32_e32 v62, 0x3fb8aa3b, v50
	v_mul_f32_e32 v50, 0xbfb8aa3b, v50
	v_exp_f32_e32 v50, v50
	v_lshlrev_b32_e32 v58, 16, v110
	v_and_b32_e32 v59, 0xffff0000, v110
	v_lshlrev_b32_e32 v60, 16, v111
	v_mul_f32_e32 v58, v50, v58
	v_add_f32_e32 v50, v51, v128
	v_sub_f32_e32 v50, v50, v69
	v_mul_f32_e32 v51, 0x3fb8aa3b, v50
	v_mul_f32_e32 v50, 0xbfb8aa3b, v50
	v_exp_f32_e32 v50, v50
	v_exp_f32_e32 v62, v62
	v_exp_f32_e32 v51, v51
	v_sub_f32_e32 v127, v71, v67
	v_mul_f32_e32 v59, v50, v59
	v_add_f32_e32 v50, v52, v76
	v_sub_f32_e32 v50, v50, v66
	v_mul_f32_e32 v52, 0x3fb8aa3b, v50
	v_mul_f32_e32 v50, 0xbfb8aa3b, v50
	v_exp_f32_e32 v50, v50
	v_exp_f32_e32 v52, v52
	v_mul_f32_e32 v127, 0x3fb8aa3b, v127
	v_cvt_pk_bf16_f32 v57, v64, v65
	v_mul_f32_e32 v60, v50, v60
	v_add_f32_e32 v50, v53, v77
	v_sub_f32_e32 v50, v50, v67
	v_mul_f32_e32 v53, 0x3fb8aa3b, v50
	v_mul_f32_e32 v50, 0xbfb8aa3b, v50
	v_exp_f32_e32 v53, v53
	v_exp_f32_e32 v50, v50
	ds_write2st64_b64 v147, v[54:55], v[56:57] offset1:34
	v_lshlrev_b32_e32 v54, 16, v112
	v_and_b32_e32 v55, 0xffff0000, v112
	v_lshlrev_b32_e32 v56, 16, v113
	v_exp_f32_e32 v127, v127
	v_and_b32_e32 v57, 0xffff0000, v113
	v_and_b32_e32 v61, 0xffff0000, v111
	v_mul_f32_e32 v54, v62, v54
	v_mul_f32_e32 v51, v51, v55
	v_mul_f32_e32 v52, v52, v56
	v_mul_f32_e32 v16, v16, v54
	v_mul_f32_e32 v55, v75, v51
	v_mul_f32_e32 v56, v119, v52
	v_mul_f32_e32 v53, v53, v57
	v_mul_f32_e32 v61, v50, v61
	v_cvt_pk_bf16_f32 v50, v54, v51
	v_cvt_pk_bf16_f32 v51, v52, v53
	v_cvt_pk_bf16_f32 v52, v16, v55
	v_mul_f32_e32 v57, v126, v53
	v_cvt_pk_bf16_f32 v53, v56, v57
	ds_write_b64 v165, v[52:53] offset:34816
	v_cvt_pk_bf16_f32 v52, v58, v59
	v_and_b32_e32 v16, 0xffff, v82
	v_mul_f32_e32 v62, v74, v58
	v_cvt_pk_bf16_f32 v53, v60, v61
	ds_write2st64_b64 v165, v[50:51], v[52:53] offset1:34
	v_cvt_pk_bf16_f32 v50, v180, v176
	v_cvt_pk_bf16_f32 v51, v131, v62
	v_lshl_or_b32 v52, v90, 16, v16
	v_add_u32_e32 v16, 0xc800, v166
	v_mul_f32_e32 v183, v127, v178
	v_mul_f32_e32 v178, v123, v132
	v_mul_f32_e32 v132, v117, v63
	v_mul_f32_e32 v63, v117, v59
	v_and_b32_e32 v53, 0xffff, v102
	v_cvt_pk_bf16_f32 v54, v181, v177
	v_cvt_pk_bf16_f32 v55, v132, v63
	ds_write2_b64 v16, v[50:51], v[54:55] offset0:128 offset1:146
	v_lshrrev_b32_e32 v50, 16, v82
	v_lshrrev_b32_e32 v51, 16, v102
	v_lshl_or_b32 v53, v120, 16, v53
	v_and_or_b32 v50, v90, s49, v50
	v_and_or_b32 v51, v120, s49, v51
	v_mul_f32_e32 v179, v127, v133
	v_mul_f32_e32 v133, v123, v64
	v_mul_f32_e32 v64, v123, v60
	ds_write2_b64 v167, v[52:53], v[50:51] offset1:18
	v_cvt_pk_bf16_f32 v51, v133, v64
	v_mul_f32_e32 v175, v127, v65
	v_mul_f32_e32 v65, v127, v61
	v_cvt_pk_bf16_f32 v50, v182, v178
	v_and_b32_e32 v52, 0xffff, v83
	v_and_b32_e32 v53, 0xffff, v103
	v_cvt_pk_bf16_f32 v54, v183, v179
	v_cvt_pk_bf16_f32 v55, v175, v65
	ds_write2_b64 v16, v[50:51], v[54:55] offset0:164 offset1:182
	v_lshrrev_b32_e32 v16, 16, v83
	v_lshrrev_b32_e32 v51, 16, v103
	v_lshl_or_b32 v52, v91, 16, v52
	v_lshl_or_b32 v53, v121, 16, v53
	v_and_or_b32 v50, v91, s49, v16
	v_and_or_b32 v51, v121, s49, v51
	ds_write2_b64 v167, v[52:53], v[50:51] offset0:36 offset1:54
	s_mov_b64 s[52:53], exec
	v_readlane_b32 s54, v255, 12
	v_readlane_b32 s55, v255, 13
	s_and_b64 s[54:55], s[52:53], s[54:55]
	s_mov_b64 exec, s[54:55]
	s_cbranch_execz .LBB0_414
	v_mul_f32_e32 v16, 0x3fb8aa3b, v72
	v_exp_f32_e32 v50, v16
	v_mul_f32_e32 v16, 0x3fb8aa3b, v73
	v_exp_f32_e32 v51, v16
	v_mul_f32_e32 v16, 0x3fb8aa3b, v70
	v_exp_f32_e32 v52, v16
	v_mul_f32_e32 v16, 0x3fb8aa3b, v71
	v_exp_f32_e32 v53, v16
	ds_write_b128 v137, v[50:53]

; __device__ __forceinline__ unsigned cvt_pk_bf16(float lo, float hi) { unsigned r; asm("v_cvt_pk_bf16_f32 %0, %1, %2" : "=v"(r) : "v"(lo), "v"(hi)); return r; }
; __device__ __forceinline__ void hg_block(ArgsP a_, int jl, unsigned char* smem) { const ArgsP a = a_;
;     ...
;         __syncthreads();
;         if (irow < len) { const float rstd = rsqrtf((RSm[irow * 2] + RSm[irow * 2 + 1]) * (1.f / 128.f) + LN_EPS);
; #pragma unroll
;             for (int vt = 0; vt < 4; ++vt) { const int v = 16 * (hw * 4 + vt) + 4 * fq; const size_t o = (size_t)(row0 + irow) * 1024 + h * 128 + v;
;                 const f32x4 gg = *(const f32x4*)(ng + h * 128 + v); const u32x2 gt = gcur[vt];
;                 const float g0 = __uint_as_float(gt.x << 16), g1 = __uint_as_float(gt.x & 0xffff0000u), g2 = __uint_as_float(gt.y << 16), g3 = __uint_as_float(gt.y & 0xffff0000u);
;                 u32x2 w; w.x = cvt_pk_bf16(O[vt][0] * rstd * gg[0] * g0, O[vt][1] * rstd * gg[1] * g1); w.y = cvt_pk_bf16(O[vt][2] * rstd * gg[2] * g2, O[vt][3] * rstd * gg[3] * g3);
;                 *(u32x2*)(ON + o) = w; } }
;         if (last) { float* dst = a->out + (sample ? O_HGS : O_HGP) + (((size_t)jl * (sample ? 128 : 8) + b) * 8 + h) * 16384; state_store<128, 128>(S, dst, 128, wid, fr, fq); }
.LBB0_438:
	s_or_b64 exec, exec, s[52:53]
	v_cmp_gt_i32_e32 vcc, s64, v134
	s_waitcnt lgkmcnt(0)
	s_barrier
	s_and_saveexec_b64 s[52:53], vcc
	s_cbranch_execz .Lhg_epi_skip
	v_add_u32_e32 v16, 0, v145
	v_add_u32_e32 v16, 0x22b00, v16
	ds_read_b64 v[66:67], v16
	s_lshl_b32 s54, s62, 8
	v_readlane_b32 s55, v255, 8
	s_add_u32 s54, s55, s54
	v_readlane_b32 s55, v255, 9
	s_waitcnt lgkmcnt(0)
	v_add_f32_e32 v16, v66, v67
	v_fmamk_f32 v16, v16, 0x3c000000, v187
	v_cmp_gt_f32_e32 vcc, s31, v16
	v_mul_f32_e32 v66, 0x4b800000, v16
	s_addc_u32 s55, s55, 0
	v_cndmask_b32_e32 v16, v16, v66, vcc
	v_rsq_f32_e32 v16, v16
	v_lshlrev_b32_e32 v74, 16, v124
	v_and_b32_e32 v75, 0xffff0000, v124
	v_lshlrev_b32_e32 v76, 16, v125
	v_mul_f32_e32 v66, 0x45800000, v16
	v_cndmask_b32_e32 v16, v16, v66, vcc
	v_add_u32_e32 v66, s63, v134
	v_ashrrev_i32_e32 v67, 31, v66
	v_lshlrev_b64 v[66:67], 11, v[66:67]
	v_lshl_add_u64 v[72:73], s[54:55], 0, v[66:67]
	s_lshl_b32 s54, s62, 9
	s_mov_b32 s55, s12
	v_lshl_add_u64 v[66:67], v[114:115], 0, s[54:55]
	v_mul_f32_e32 v62, v62, v16
	v_mul_f32_e32 v63, v63, v16
	v_and_b32_e32 v77, 0xffff0000, v125
	v_mov_b32_e32 v123, v17
	v_mul_f32_e32 v58, v58, v16
	v_mul_f32_e32 v59, v59, v16
	v_mul_f32_e32 v54, v54, v16
	v_mul_f32_e32 v55, v55, v16
	v_mul_f32_e32 v50, v50, v16
	v_mul_f32_e32 v51, v51, v16
	s_waitcnt vmcnt(0)
	v_mul_f32_e32 v62, v202, v62
	v_mul_f32_e32 v63, v203, v63
	v_mul_f32_e32 v62, v62, v74
	v_mul_f32_e32 v63, v63, v75
	v_cvt_pk_bf16_f32 v68, v62, v63
	v_mul_f32_e32 v62, v64, v16
	v_mul_f32_e32 v63, v65, v16
	v_mul_f32_e32 v62, v204, v62
	v_mul_f32_e32 v63, v205, v63
	v_mul_f32_e32 v62, v62, v76
	v_mul_f32_e32 v63, v63, v77
	v_cvt_pk_bf16_f32 v69, v62, v63
	v_lshl_add_u64 v[62:63], v[72:73], 0, v[122:123]
	global_store_dwordx2 v[62:63], v[68:69], off
	v_lshlrev_b32_e32 v64, 16, v104
	v_and_b32_e32 v65, 0xffff0000, v104
	v_lshlrev_b32_e32 v72, 16, v105
	v_and_b32_e32 v73, 0xffff0000, v105
	v_mul_f32_e32 v58, v206, v58
	v_mul_f32_e32 v59, v207, v59
	v_mul_f32_e32 v58, v58, v64
	v_mul_f32_e32 v59, v59, v65
	v_cvt_pk_bf16_f32 v58, v58, v59
	v_mul_f32_e32 v59, v60, v16
	v_mul_f32_e32 v59, v208, v59
	v_mul_f32_e32 v60, v61, v16
	v_mul_f32_e32 v59, v59, v72
	v_mul_f32_e32 v60, v209, v60
	v_mul_f32_e32 v60, v60, v73
	v_cvt_pk_bf16_f32 v59, v59, v60
	global_store_dwordx2 v[62:63], v[58:59], off offset:32
	v_lshlrev_b32_e32 v64, 16, v94
	v_and_b32_e32 v65, 0xffff0000, v94
	v_lshlrev_b32_e32 v68, 16, v95
	v_and_b32_e32 v69, 0xffff0000, v95
	v_mul_f32_e32 v54, v54, v210
	v_mul_f32_e32 v55, v55, v211
	v_mul_f32_e32 v54, v54, v64
	v_mul_f32_e32 v55, v55, v65
	v_cvt_pk_bf16_f32 v54, v54, v55
	v_mul_f32_e32 v55, v56, v16
	v_mul_f32_e32 v55, v55, v212
	v_mul_f32_e32 v56, v57, v16
	v_mul_f32_e32 v55, v55, v68
	v_mul_f32_e32 v56, v56, v213
	v_mul_f32_e32 v56, v56, v69
	v_cvt_pk_bf16_f32 v55, v55, v56
	global_store_dwordx2 v[62:63], v[54:55], off offset:64
	v_lshlrev_b32_e32 v58, 16, v84
	v_and_b32_e32 v59, 0xffff0000, v84
	v_lshlrev_b32_e32 v60, 16, v85
	v_and_b32_e32 v61, 0xffff0000, v85
	v_mul_f32_e32 v50, v50, v214
	v_mul_f32_e32 v51, v51, v215
	v_mul_f32_e32 v50, v50, v58
	v_mul_f32_e32 v51, v51, v59
	v_cvt_pk_bf16_f32 v50, v50, v51
	v_mul_f32_e32 v51, v52, v16
	v_mul_f32_e32 v51, v51, v216
	v_mul_f32_e32 v16, v53, v16
	v_mul_f32_e32 v51, v51, v60
	v_mul_f32_e32 v16, v16, v217
	v_mul_f32_e32 v16, v16, v61
	v_cvt_pk_bf16_f32 v51, v51, v16
	global_store_dwordx2 v[62:63], v[50:51], off offset:96
	s_branch .LBB0_440
.Lhg_epi_skip:
	s_waitcnt vmcnt(0)
.LBB0_440:
	s_or_b64 exec, exec, s[52:53]
	s_cmp_lg_u32 s61, 32
	s_cselect_b64 s[52:53], -1, 0
	s_and_b64 s[50:51], s[50:51], s[52:53]
	s_and_b64 vcc, exec, s[50:51]
	s_cbranch_vccnz .LBB0_390
	s_load_dwordx2 s[50:51], s[4:5], 0xd8
	v_readlane_b32 s52, v255, 33
	v_lshlrev_b32_e32 v16, 2, v92
	s_waitcnt lgkmcnt(0)
	s_add_u32 s52, s50, s52
	s_addc_u32 s53, s51, 0
	s_ashr_i32 s51, s48, 31
	s_add_u32 s50, s42, s48
	s_addc_u32 s51, s43, s51
	s_lshl_b64 s[50:51], s[50:51], 19
	s_add_u32 s48, s52, s50
	s_addc_u32 s51, s53, s51
	s_lshl_b32 s50, s62, 16
	s_add_u32 s50, s48, s50
	s_addc_u32 s51, s51, 0
	v_lshl_add_u64 v[50:51], s[50:51], 0, v[96:97]
	v_lshl_add_u64 v[50:51], v[50:51], 0, v[16:17]
	global_store_dword v[50:51], v18, off
	global_store_dword v[50:51], v19, off offset:512
	global_store_dword v[50:51], v20, off offset:1024
	global_store_dword v[50:51], v21, off offset:1536
	global_store_dword v[50:51], v22, off offset:64
	global_store_dword v[50:51], v23, off offset:576
	global_store_dword v[50:51], v24, off offset:1088
	global_store_dword v[50:51], v25, off offset:1600
	global_store_dword v[50:51], v26, off offset:128
	global_store_dword v[50:51], v27, off offset:640
	global_store_dword v[50:51], v28, off offset:1152
	global_store_dword v[50:51], v29, off offset:1664
	global_store_dword v[50:51], v30, off offset:192
	global_store_dword v[50:51], v31, off offset:704
	global_store_dword v[50:51], v32, off offset:1216
	global_store_dword v[50:51], v33, off offset:1728
	global_store_dword v[50:51], v34, off offset:256
	global_store_dword v[50:51], v35, off offset:768
	global_store_dword v[50:51], v36, off offset:1280
	global_store_dword v[50:51], v37, off offset:1792
	global_store_dword v[50:51], v38, off offset:320
	global_store_dword v[50:51], v39, off offset:832
	global_store_dword v[50:51], v40, off offset:1344
	global_store_dword v[50:51], v41, off offset:1856
	global_store_dword v[50:51], v42, off offset:384
	global_store_dword v[50:51], v43, off offset:896
	global_store_dword v[50:51], v44, off offset:1408
	global_store_dword v[50:51], v45, off offset:1920
	global_store_dword v[50:51], v46, off offset:448
	global_store_dword v[50:51], v47, off offset:960
	global_store_dword v[50:51], v48, off offset:1472
	global_store_dword v[50:51], v49, off offset:1984
	s_branch .LBB0_390
